# stack34 with the per-phase workgroup stagger halved (s_sleep 0x55 -> 0x2b)
# speedup vs baseline: 1.0117x; 1.0117x over previous
.LBB0_149:
	s_add_i32 s6, s6, -1
	s_cmp_eq_u32 s6, 0
	s_sleep 0x2b
	s_cbranch_scc0 .LBB0_149

.LBB0_224:
	s_add_i32 s2, s2, -1
	s_cmp_eq_u32 s2, 0
	s_sleep 0x2b
	s_cbranch_scc0 .LBB0_224
